# combined: best + swiglu epilogue deferred into the next unit's first K-iteration + depth-2 prefetch in the x conversion loop
# speedup vs baseline: 1.0052x; 1.0052x over previous
; __device__ __forceinline__ void xcd_barrier(const XcdBarrier& b) {
;     asm volatile("s_waitcnt vmcnt(0)" ::: "memory");
;     __syncthreads();
;     if (threadIdx.x == 0) {
;         unsigned* bar = b.bar;
;         __builtin_amdgcn_s_waitcnt(0);
;         unsigned nloc = b.st[0], nx = b.st[1];
;         if (nloc == 0u) { xcd_barrier_complete(bar, b.x, nloc, nx); b.st[0] = nloc; b.st[1] = nx; }
; __global__ void __launch_bounds__(NTHREADS, 2) fwd_megakernel(Args args) {
;     ...
;         default: break;
;         }
;         if (ph < 10) { if (__builtin_expect(G > 4096, 0)) grid.sync(); else xcd_barrier(bar); }
.LBB0_586:
	s_mov_b32 s101, 0
	s_cmp_eq_u32 s88, 10
	s_cbranch_scc1 .LBB0_9
	s_cmpk_lt_i32 s89, 0x1001
	s_cbranch_scc0 .LBB0_655
	s_waitcnt vmcnt(0)
	s_waitcnt vmcnt(0) lgkmcnt(0)
	s_barrier
	s_mov_b64 s[0:1], exec
	v_readlane_b32 s4, v253, 6
	v_readlane_b32 s5, v253, 7
	s_and_b64 s[4:5], s[0:1], s[4:5]
	s_mov_b64 exec, s[4:5]
	s_cbranch_execz .LBB0_644
	v_readlane_b32 s4, v254, 36
	s_waitcnt vmcnt(0) expcnt(0) lgkmcnt(0)
	s_nop 0
	v_mov_b32_e32 v0, s4
	ds_read_b32 v3, v0
	v_readlane_b32 s4, v254, 37
	s_waitcnt lgkmcnt(0)
	v_cmp_ne_u32_e32 vcc, 0, v3
	v_mov_b32_e32 v0, s4
	ds_read_b32 v2, v0
	s_cbranch_vccnz .LBB0_608
	s_mov_b32 s4, 1
	s_branch .LBB0_592
